# 64-bit accumulator clears extended to the remaining GEMM tile loop and shorter clear runs
# baseline (speedup 1.0000x reference)
.LBB0_734:
	s_abs_i32 s1, s74
	v_readlane_b32 s2, v255, 40
	s_mul_hi_u32 s2, s1, s2
	s_mul_i32 s3, s2, s41
	s_sub_i32 s1, s1, s3
	s_ashr_i32 s0, s74, 31
	s_add_i32 s3, s2, 1
	s_sub_i32 s8, s1, s41
	s_cmp_ge_u32 s1, s41
	s_cselect_b32 s2, s3, s2
	s_cselect_b32 s1, s8, s1
	s_add_i32 s3, s2, 1
	s_cmp_ge_u32 s1, s41
	s_cselect_b32 s1, s3, s2
	s_xor_b32 s1, s1, s0
	s_sub_i32 s1, s1, s0
	s_and_b32 s0, s1, 3
	s_ashr_i32 s1, s1, 2
	s_sub_i32 s75, 1, s1
	s_lshl_b32 s2, s21, 6
	v_mov_b32_e32 v10, v207
	s_cmp_lt_i32 s21, 4
	s_cselect_b32 s22, s7, s6
	v_lshlrev_b32_e32 v0, 4, v10
	v_and_b32_e32 v66, 0x70, v0
	s_add_i32 s22, s22, s2
	v_mov_b32_e32 v0, v207
	s_barrier
	s_cmp_lg_u32 s1, 1
	v_and_b32_e32 v6, 63, v0
	v_or_b32_e32 v1, s22, v6
	s_movk_i32 s2, 0x1200
	s_cselect_b64 s[96:97], -1, 0
	s_lshl_b32 s20, s0, 7
	s_lshl_b32 s26, s0, 8
	v_mul_lo_u32 v128, v1, s2
	s_cmp_eq_u32 s1, 1
	s_movk_i32 s1, 0x800
	v_ashrrev_i32_e32 v0, 2, v0
	v_lshl_add_u64 v[2:3], v[128:129], 1, s[36:37]
	s_cselect_b32 s94, s1, 0x1c00
	s_mov_b32 s95, 0
	v_and_b32_e32 v0, -16, v0
	v_lshl_add_u64 v[2:3], v[2:3], 0, s[94:95]
	v_lshl_add_u64 v[2:3], v[2:3], 0, s[26:27]
	v_ashrrev_i32_e32 v1, 31, v0
	v_lshl_add_u64 v[4:5], v[0:1], 1, v[2:3]
	s_movk_i32 s8, 0x90
	v_lshlrev_b32_e32 v12, 1, v6
	v_mul_lo_u32 v13, v0, s8
	global_load_dwordx4 v[0:3], v[4:5], off
	s_nop 0
	global_load_dwordx4 v[4:7], v[4:5], off offset:16
	v_ashrrev_i32_e32 v67, 3, v10
	v_mov_b64_e32 v[8:9], s[36:37]
	v_readlane_b32 s4, v252, 12
	v_add_u32_e32 v64, s22, v67
	v_mad_i64_i32 v[68:69], s[2:3], v64, s14, v[8:9]
	v_add3_u32 v14, s4, v12, v13
	v_add3_u32 v12, s4, v13, v12
	s_cselect_b32 s94, 0, 0x1000
	v_lshlrev_b32_e32 v128, 1, v66
	v_ashrrev_i32_e32 v11, 6, v10
	v_and_b32_e32 v92, 31, v10
	v_and_b32_e32 v94, 3, v11
	s_lshl_b32 s1, s75, 3
	s_lshl_b32 s2, s0, 1
	s_or_b32 s23, s1, s2
	v_bfe_u32 v93, v10, 5, 1
	s_cmp_gt_i32 s21, 3
	s_cselect_b32 s1, 0x87, 3
	v_lshl_add_u32 v95, v66, 2, 0
	v_readlane_b32 s5, v255, 1
	v_bfi_b32 v8, -16, v67, v10
	v_cvt_f32_ubyte0_e32 v96, s0
	v_ashrrev_i32_e32 v65, 31, v64
	s_mov_b64 s[92:93], -1
	s_waitcnt vmcnt(0) lgkmcnt(0)
	ds_write_b16 v14, v0
	ds_write_b16_d16_hi v12, v0 offset:144
	ds_write_b16 v14, v1 offset:288
	ds_write_b16_d16_hi v12, v1 offset:432
	ds_write_b16 v14, v2 offset:576
	ds_write_b16_d16_hi v12, v2 offset:720
	ds_write_b16 v14, v3 offset:864
	ds_write_b16_d16_hi v12, v3 offset:1008
	ds_write_b16 v14, v4 offset:1152
	ds_write_b16_d16_hi v12, v4 offset:1296
	ds_write_b16 v14, v5 offset:1440
	ds_write_b16_d16_hi v12, v5 offset:1584
	ds_write_b16 v14, v6 offset:1728
	ds_write_b16_d16_hi v12, v6 offset:1872
	ds_write_b16 v14, v7 offset:2016
	ds_write_b16_d16_hi v12, v7 offset:2160
	v_lshl_add_u64 v[0:1], v[68:69], 0, s[94:95]
	v_lshl_add_u64 v[0:1], v[0:1], 0, s[26:27]
	v_lshl_add_u64 v[4:5], v[0:1], 0, v[128:129]
	global_load_dwordx4 v[0:3], v[4:5], off
	s_nop 0
	global_load_dwordx4 v[4:7], v[4:5], off offset:16
	s_sub_i32 s94, s1, s21
	v_readlane_b32 s1, v255, 0
	s_add_u32 s2, s36, s26
	s_addc_u32 s3, s37, 0
	s_waitcnt vmcnt(0) lgkmcnt(0)
	v_lshlrev_b32_e32 v70, 16, v0
	v_lshlrev_b32_e32 v78, 16, v4
	v_and_b32_e32 v79, 0xffff0000, v4
	v_lshl_or_b32 v4, v94, 5, v92
	v_and_b32_e32 v71, 0xffff0000, v0
	v_lshlrev_b32_e32 v72, 16, v1
	v_and_b32_e32 v73, 0xffff0000, v1
	v_lshlrev_b32_e32 v0, 8, v4
	v_mov_b32_e32 v1, v129
	v_lshlrev_b32_e32 v74, 16, v2
	v_and_b32_e32 v75, 0xffff0000, v2
	v_lshlrev_b32_e32 v76, 16, v3
	v_and_b32_e32 v77, 0xffff0000, v3
	v_lshl_add_u64 v[0:1], s[84:85], 0, v[0:1]
	v_lshlrev_b32_e32 v2, 4, v93
	v_mov_b32_e32 v3, v129
	v_lshl_add_u64 v[86:87], v[0:1], 0, v[2:3]
	v_add_u32_e32 v3, s4, v2
	s_movk_i32 s4, 0x110
	v_lshlrev_b32_e32 v80, 16, v5
	v_and_b32_e32 v81, 0xffff0000, v5
	v_sub_u32_e32 v0, v95, v128
	v_add_u32_e32 v1, s5, v2
	v_add_u32_e32 v5, s1, v2
	v_mul_lo_u32 v2, v67, s4
	v_add_u32_e32 v97, v0, v2
	v_add3_u32 v98, s1, v128, v2
	v_and_b32_e32 v2, 48, v10
	v_add_u32_e32 v2, 0, v2
	v_mad_u64_u32 v[88:89], s[0:1], v8, s4, v[2:3]
	v_lshrrev_b32_e32 v8, 2, v10
	v_and_b32_e32 v8, 12, v8
	v_lshlrev_b32_e32 v84, 16, v7
	v_and_b32_e32 v85, 0xffff0000, v7
	v_lshlrev_b32_e32 v0, 5, v11
	v_and_b32_e32 v7, 15, v10
	v_and_or_b32 v8, v67, -16, v8
	v_and_or_b32 v0, v0, 32, v7
	v_or_b32_e32 v13, 1, v8
	v_or_b32_e32 v14, 2, v8
	v_or_b32_e32 v15, 3, v8
	s_movk_i32 s0, 0xffe0
	v_mul_u32_u24_e32 v7, 0x110, v0
	v_lshl_add_u32 v11, v0, 1, s5
	v_cmp_ge_i32_e64 s[42:43], v0, v8
	v_cmp_le_i32_e64 s[44:45], v0, v8
	v_cmp_gt_i32_e64 s[46:47], v0, v8
	v_cmp_le_i32_e64 s[48:49], v0, v13
	v_cmp_ge_i32_e64 s[50:51], v0, v14
	v_cmp_le_i32_e64 s[52:53], v0, v14
	v_cmp_ge_i32_e64 s[54:55], v0, v15
	v_cmp_le_i32_e64 s[56:57], v0, v15
	v_or_b32_e32 v0, 16, v0
	v_bfi_b32 v9, s0, v67, v10
	v_mul_lo_u32 v12, v8, s8
	v_lshlrev_b32_e32 v16, 1, v0
	v_lshlrev_b32_e32 v82, 16, v6
	v_and_b32_e32 v83, 0xffff0000, v6
	v_lshlrev_b32_e32 v6, 9, v67
	v_mul_lo_u32 v10, v9, s8
	v_mul_u32_u24_e32 v4, 0x90, v4
	v_mul_lo_u32 v9, v9, s4
	v_cmp_ge_i32_e64 s[58:59], v0, v8
	v_cmp_le_i32_e64 s[60:61], v0, v8
	v_add3_u32 v99, s5, v12, v16
	v_cmp_gt_i32_e64 s[62:63], v0, v8
	v_cmp_le_i32_e64 s[64:65], v0, v13
	v_cmp_ge_i32_e64 s[66:67], v0, v14
	v_cmp_le_i32_e64 s[68:69], v0, v14
	v_cmp_ge_i32_e64 s[70:71], v0, v15
	v_cmp_le_i32_e64 s[72:73], v0, v15
	v_mov_b32_e32 v0, 0
	v_and_b32_e32 v89, 0xffffffe0, v67
	v_add_u32_e32 v100, 0x90, v99
	v_add_u32_e32 v101, 0x120, v99
	v_add_u32_e32 v102, 0x1b0, v99
	v_add_u32_e32 v103, v95, v6
	v_add_u32_e32 v104, v2, v7
	v_add_u32_e32 v105, v11, v12
	v_add_u32_e32 v106, v1, v10
	v_add_u32_e32 v107, v3, v4
	v_add_u32_e32 v108, v5, v9
	v_mov_b32_e32 v1, v0
	v_mov_b64_e32 v[2:3], 0
	v_mov_b64_e32 v[4:5], 0
	v_mov_b64_e32 v[6:7], 0
	v_mov_b64_e32 v[8:9], 0
	v_mov_b64_e32 v[10:11], 0
	v_mov_b64_e32 v[12:13], 0
	v_mov_b64_e32 v[14:15], 0
	s_branch .LBB0_736

.LBB0_1018:
	s_ashr_i32 s55, s54, 31
	s_lshl_b64 s[8:9], s[54:55], 19
	v_readlane_b32 s20, v251, 3
	v_readlane_b32 s21, v251, 4
	s_add_u32 s58, s20, s8
	s_addc_u32 s59, s21, s9
	s_ashr_i32 s53, s52, 31
	s_lshl_b64 s[8:9], s[52:53], 19
	s_add_u32 s60, s5, s8
	v_mov_b32_e32 v127, 0
	s_addc_u32 s61, s6, s9
	s_andn2_b64 vcc, exec, s[0:1]
	v_mov_b32_e32 v126, v127
	v_mov_b64_e32 v[124:125], 0
	v_mov_b64_e32 v[122:123], 0
	v_mov_b64_e32 v[120:121], 0
	v_mov_b64_e32 v[110:111], 0
	v_mov_b64_e32 v[108:109], 0
	v_mov_b64_e32 v[106:107], 0
	s_waitcnt lgkmcnt(0)
	v_mov_b64_e32 v[104:105], 0
	v_mov_b64_e32 v[94:95], 0
	v_mov_b64_e32 v[92:93], 0
	v_mov_b64_e32 v[90:91], 0
	v_mov_b64_e32 v[88:89], 0
	v_mov_b64_e32 v[78:79], 0
	v_mov_b64_e32 v[76:77], 0
	v_mov_b64_e32 v[74:75], 0
	v_mov_b64_e32 v[72:73], 0
	v_mov_b64_e32 v[118:119], 0
	v_mov_b64_e32 v[116:117], 0
	v_mov_b64_e32 v[114:115], 0
	v_mov_b64_e32 v[112:113], 0
	v_mov_b64_e32 v[102:103], 0
	v_mov_b64_e32 v[100:101], 0
	v_mov_b64_e32 v[98:99], 0
	v_mov_b64_e32 v[96:97], 0
	v_mov_b64_e32 v[86:87], 0
	v_mov_b64_e32 v[84:85], 0
	v_mov_b64_e32 v[82:83], 0
	v_mov_b64_e32 v[80:81], 0
	v_mov_b64_e32 v[70:71], 0
	v_mov_b64_e32 v[68:69], 0
	v_mov_b64_e32 v[66:67], 0
	v_mov_b64_e32 v[64:65], 0
	v_mov_b64_e32 v[62:63], 0
	v_mov_b64_e32 v[60:61], 0
	v_mov_b64_e32 v[58:59], 0
	v_mov_b64_e32 v[56:57], 0
	v_mov_b64_e32 v[46:47], 0
	v_mov_b64_e32 v[44:45], 0
	v_mov_b64_e32 v[42:43], 0
	v_mov_b64_e32 v[40:41], 0
	v_mov_b64_e32 v[30:31], 0
	v_mov_b64_e32 v[28:29], 0
	v_mov_b64_e32 v[26:27], 0
	v_mov_b64_e32 v[24:25], 0
	v_mov_b64_e32 v[14:15], 0
	v_mov_b64_e32 v[12:13], 0
	v_mov_b64_e32 v[10:11], 0
	v_mov_b64_e32 v[8:9], 0
	v_mov_b64_e32 v[54:55], 0
	v_mov_b64_e32 v[52:53], 0
	v_mov_b64_e32 v[50:51], 0
	v_mov_b64_e32 v[48:49], 0
	v_mov_b64_e32 v[38:39], 0
	v_mov_b64_e32 v[36:37], 0
	v_mov_b64_e32 v[34:35], 0
	v_mov_b64_e32 v[32:33], 0
	v_mov_b64_e32 v[22:23], 0
	v_mov_b64_e32 v[20:21], 0
	v_mov_b64_e32 v[18:19], 0
	v_mov_b64_e32 v[16:17], 0
	v_mov_b64_e32 v[6:7], 0
	v_mov_b64_e32 v[4:5], 0
	v_mov_b64_e32 v[2:3], 0
	v_mov_b64_e32 v[0:1], 0
	s_cbranch_vccnz .LBB0_1022
	v_mov_b64_e32 v[0:1], 0x108
	v_cmp_lt_i64_e32 vcc, s[50:51], v[0:1]
	s_and_b64 s[8:9], vcc, exec
	s_cselect_b32 s3, s59, s49
	s_cselect_b32 s8, s58, s48
	s_cselect_b32 s9, s61, s47
	s_cselect_b32 s19, s60, s46
	s_add_u32 s20, s46, 0x100
	s_addc_u32 s21, s47, 0
	s_add_u32 s46, s48, 0x40080
	v_mov_b32_e32 v0, 0
	s_addc_u32 s47, s49, 0
	s_mov_b32 s22, 0
	v_mov_b32_e32 v1, v0
	v_mov_b64_e32 v[2:3], 0
	v_mov_b64_e32 v[4:5], 0
	v_mov_b64_e32 v[6:7], 0
	v_mov_b64_e32 v[16:17], 0
	v_mov_b64_e32 v[18:19], 0
	v_mov_b64_e32 v[20:21], 0
	v_mov_b64_e32 v[22:23], 0
	v_mov_b64_e32 v[32:33], 0
	v_mov_b64_e32 v[34:35], 0
	v_mov_b64_e32 v[36:37], 0
	v_mov_b64_e32 v[38:39], 0
	v_mov_b64_e32 v[48:49], 0
	v_mov_b64_e32 v[50:51], 0
	v_mov_b64_e32 v[52:53], 0
	v_mov_b64_e32 v[54:55], 0
	v_mov_b64_e32 v[8:9], 0
	v_mov_b64_e32 v[10:11], 0
	v_mov_b64_e32 v[12:13], 0
	v_mov_b64_e32 v[14:15], 0
	v_mov_b64_e32 v[24:25], 0
	v_mov_b64_e32 v[26:27], 0
	v_mov_b64_e32 v[28:29], 0
	v_mov_b64_e32 v[30:31], 0
	v_mov_b64_e32 v[40:41], 0
	v_mov_b64_e32 v[42:43], 0
	v_mov_b64_e32 v[44:45], 0
	v_mov_b64_e32 v[46:47], 0
	v_mov_b64_e32 v[56:57], 0
	v_mov_b64_e32 v[58:59], 0
	v_mov_b64_e32 v[60:61], 0
	v_mov_b64_e32 v[62:63], 0
	v_mov_b64_e32 v[64:65], 0
	v_mov_b64_e32 v[66:67], 0
	v_mov_b64_e32 v[68:69], 0
	v_mov_b64_e32 v[70:71], 0
	v_mov_b64_e32 v[80:81], 0
	v_mov_b64_e32 v[82:83], 0
	v_mov_b64_e32 v[84:85], 0
	v_mov_b64_e32 v[86:87], 0
	v_mov_b64_e32 v[96:97], 0
	v_mov_b64_e32 v[98:99], 0
	v_mov_b64_e32 v[100:101], 0
	v_mov_b64_e32 v[102:103], 0
	v_mov_b64_e32 v[112:113], 0
	v_mov_b64_e32 v[114:115], 0
	v_mov_b64_e32 v[116:117], 0
	v_mov_b64_e32 v[118:119], 0
	v_mov_b64_e32 v[72:73], 0
	v_mov_b64_e32 v[74:75], 0
	v_mov_b64_e32 v[76:77], 0
	v_mov_b64_e32 v[78:79], 0
	v_mov_b64_e32 v[88:89], 0
	v_mov_b64_e32 v[90:91], 0
	v_mov_b64_e32 v[92:93], 0
	v_mov_b64_e32 v[94:95], 0
	v_mov_b64_e32 v[104:105], 0
	v_mov_b64_e32 v[106:107], 0
	v_mov_b64_e32 v[108:109], 0
	v_mov_b64_e32 v[110:111], 0
	v_mov_b64_e32 v[120:121], 0
	v_mov_b64_e32 v[122:123], 0
	v_mov_b64_e32 v[124:125], 0
	v_mov_b64_e32 v[126:127], 0

.LBB0_1879:
	s_or_b64 exec, exec, s[8:9]
	s_mul_i32 s2, s20, 0x108000
	s_mul_hi_u32 s3, s20, 0x108000
	s_add_u32 s2, s48, s2
	s_addc_u32 s3, s49, s3
	v_ashrrev_i32_e32 v17, 3, v10
	v_and_b32_e32 v6, 7, v10
	v_mov_b64_e32 v[4:5], s[2:3]
	s_movk_i32 s2, 0x4200
	v_mad_i64_i32 v[4:5], s[2:3], v17, s2, v[4:5]
	v_lshlrev_b32_e32 v128, 4, v6
	v_lshl_add_u64 v[4:5], v[4:5], 0, v[128:129]
	global_load_dwordx4 v[4:7], v[4:5], off
	s_movk_i32 s2, 0xd0
	v_mul_lo_u32 v113, v11, s2
	v_lshlrev_b32_e32 v114, 4, v14
	v_add3_u32 v14, 0, v113, v114
	v_lshlrev_b32_e32 v115, 4, v16
	s_waitcnt vmcnt(0) lgkmcnt(0)
	ds_write_b128 v14, v[0:3]
	s_and_saveexec_b64 s[2:3], s[0:1]
	s_xor_b64 s[0:1], exec, s[2:3]
	v_lshlrev_b32_e32 v115, 4, v16
	s_or_saveexec_b64 s[0:1], s[0:1]
	s_movk_i32 s2, 0xd0
	v_mul_lo_u32 v116, v15, s2
	s_xor_b64 exec, exec, s[0:1]
	v_add3_u32 v0, 0, v116, v115
	ds_write_b128 v0, v[88:91]
	s_or_b64 exec, exec, s[0:1]
	s_movk_i32 s0, 0x4200
	v_mad_i64_i32 v[0:1], s[0:1], v17, s0, 0
	s_movk_i32 s0, 0x90
	s_nop 0
	v_mul_lo_u32 v118, v17, s0
	v_add3_u32 v2, 0, v118, v128
	v_cmp_lt_i32_e64 s[0:1], v223, v222
	ds_write_b128 v2, v[4:7] offset:13312
	v_and_b32_e32 v105, 31, v10
	v_cndmask_b32_e64 v2, v205, v223, s[0:1]
	v_mad_u64_u32 v[0:1], s[0:1], s41, v236, v[0:1]
	v_lshlrev_b32_e32 v103, 2, v2
	v_mad_i64_i32 v[2:3], s[0:1], v15, s11, 0
	v_lshl_add_u64 v[0:1], v[0:1], 0, v[128:129]
	v_lshl_add_u64 v[106:107], s[50:51], 0, v[0:1]
	v_mad_u64_u32 v[0:1], s[0:1], s41, v237, v[2:3]
	v_lshl_add_u64 v[0:1], v[12:13], 1, v[0:1]
	v_lshl_add_u64 v[108:109], s[52:53], 0, v[0:1]
	v_mad_i64_i32 v[0:1], s[0:1], v11, s11, 0
	v_mad_u64_u32 v[0:1], s[0:1], s41, v237, v[0:1]
	v_lshl_add_u64 v[0:1], v[8:9], 1, v[0:1]
	v_mov_b32_e32 v120, 0
	v_ashrrev_i32_e32 v101, 31, v100
	v_lshlrev_b32_e32 v102, 3, v18
	v_mul_u32_u24_e32 v117, 0xd0, v105
	v_mul_u32_u24_e32 v119, 0x90, v105
	s_mov_b32 s2, 1
	v_lshl_add_u64 v[110:111], s[52:53], 0, v[0:1]
	v_mov_b32_e32 v112, 0xf149f2ca
	v_mov_b32_e32 v16, 0
	v_mov_b32_e32 v17, v120
	v_mov_b64_e32 v[18:19], 0
	v_mov_b64_e32 v[20:21], 0
	v_mov_b64_e32 v[22:23], 0
	v_mov_b64_e32 v[24:25], 0
	v_mov_b64_e32 v[26:27], 0
	v_mov_b64_e32 v[28:29], 0
	v_mov_b64_e32 v[30:31], 0
	v_mov_b32_e32 v0, 0
	v_mov_b32_e32 v1, v120
	v_mov_b64_e32 v[2:3], 0
	v_mov_b64_e32 v[4:5], 0
	v_mov_b64_e32 v[6:7], 0
	v_mov_b64_e32 v[8:9], 0
	v_mov_b64_e32 v[10:11], 0
	v_mov_b64_e32 v[12:13], 0
	v_mov_b64_e32 v[14:15], 0
	s_waitcnt lgkmcnt(0)
	s_barrier
	global_load_dwordx4 v[96:99], v[110:111], off
	s_and_saveexec_b64 s[0:1], vcc
	s_cbranch_execz .LBB0_1886
	s_branch .LBB0_1885
